# all kept edits stacked: v41 + DPP row reductions in P0/P10 + merged staging waits + e32 adds + filled trans-hazard nop slots
# baseline (speedup 1.0000x reference)
.LBB0_441:
	s_and_b32 s48, s33, 2
	s_add_i32 s4, s33, -1
	s_and_b32 s49, s4, 3
	s_mul_i32 s4, s48, 0x4800
	v_add_u32_e32 v168, s4, v184
	s_cmp_eq_u32 s33, 0
	ds_read_b128 v[164:167], v168 offset:96
	s_cselect_b64 s[6:7], -1, 0
	s_mulk_i32 s49, 0x4800
	s_and_b64 s[4:5], s[6:7], exec
	s_cselect_b32 s4, 0, s49
	v_exp_f32_e32 v64, v64
	v_exp_f32_e32 v65, v65
	v_add_u32_e32 v84, s4, v184
	v_add_f32_e32 v113, v65, v64
	v_cvt_pk_bf16_f32 v112, v64, v65
	ds_read_b128 v[186:189], v84 offset:9280
	ds_read_b128 v[190:193], v84 offset:9312
	ds_read_b128 v[194:197], v84 offset:13888
	ds_read_b128 v[198:201], v84 offset:13920
	v_mfma_f32_32x32x16_bf16 v[80:95], v[80:83], v[148:151], 0
	v_exp_f32_e32 v64, v66
	v_exp_f32_e32 v65, v67
	v_add_f32_e32 v66, v64, v113
	v_add_f32_e32 v66, v65, v66
	v_cvt_pk_bf16_f32 v113, v64, v65
	v_mfma_f32_32x32x16_bf16 v[80:95], v[108:111], v[152:155], v[80:95]
	v_exp_f32_e32 v64, v68
	v_exp_f32_e32 v65, v69
	v_add_f32_e32 v66, v64, v66
	v_cvt_pk_bf16_f32 v114, v64, v65
	v_add_f32_e32 v64, v65, v66
	v_mfma_f32_32x32x16_bf16 v[80:95], v[104:107], v[156:159], v[80:95]
	v_exp_f32_e32 v65, v70
	v_exp_f32_e32 v66, v71
	v_add_f32_e32 v64, v65, v64
	v_cvt_pk_bf16_f32 v115, v65, v66
	v_add_f32_e32 v64, v66, v64
	s_waitcnt lgkmcnt(4)
	v_mfma_f32_32x32x16_bf16 v[80:95], v[164:167], v[160:163], v[80:95]
	v_exp_f32_e32 v65, v72
	v_exp_f32_e32 v66, v73
	v_add_f32_e32 v64, v65, v64
	v_cvt_pk_bf16_f32 v104, v65, v66
	v_add_f32_e32 v64, v66, v64
	s_waitcnt lgkmcnt(0)
	v_mfma_f32_32x32x16_bf16 v[16:31], v[186:189], v[96:99], v[16:31]
	v_exp_f32_e32 v65, v74
	v_exp_f32_e32 v66, v75
	v_add_f32_e32 v64, v65, v64
	v_cvt_pk_bf16_f32 v105, v65, v66
	v_add_f32_e32 v64, v66, v64
	v_mfma_f32_32x32x16_bf16 v[16:31], v[190:193], v[100:103], v[16:31]
	v_exp_f32_e32 v65, v76
	v_exp_f32_e32 v66, v77
	v_add_f32_e32 v64, v65, v64
	v_cvt_pk_bf16_f32 v106, v65, v66
	v_add_f32_e32 v64, v66, v64
	v_mfma_f32_32x32x16_bf16 v[0:15], v[194:197], v[96:99], v[0:15]
	v_exp_f32_e32 v65, v78
	v_exp_f32_e32 v66, v79
	v_add_f32_e32 v64, v65, v64
	v_cvt_pk_bf16_f32 v107, v65, v66
	v_add_f32_e32 v185, v66, v64
	v_exp_f32_e32 v68, v80
	v_exp_f32_e32 v69, v81
	v_mfma_f32_32x32x16_bf16 v[0:15], v[198:201], v[100:103], v[0:15]
	v_add_f32_e32 v80, v69, v68
	v_cvt_pk_bf16_f32 v96, v68, v69
	ds_read_b128 v[64:67], v168 offset:4608
	ds_read_b128 v[164:167], v168 offset:4640
	ds_read_b128 v[108:111], v168 offset:4672
	v_cmp_nge_f32_e64 s[4:5], s62, v185
	v_cmp_gt_f32_e32 vcc, s75, v185
	s_and_b64 vcc, s[6:7], vcc
	s_or_b64 s[4:5], s[4:5], vcc
	ds_read_b128 v[186:189], v168 offset:4704
	s_waitcnt lgkmcnt(1)
	v_mfma_f32_32x32x16_bf16 v[64:79], v[64:67], v[116:119], 0
	ds_read_b128 v[190:193], v168 offset:9216
	ds_read_b128 v[194:197], v168 offset:9248
	ds_read_b128 v[198:201], v168 offset:13824
	ds_read_b128 v[230:233], v168 offset:13856
	v_exp_f32_e32 v81, v82
	v_exp_f32_e32 v82, v83
	v_add_f32_e32 v80, v81, v80
	v_add_f32_e32 v80, v82, v80
	v_cvt_pk_bf16_f32 v97, v81, v82
	v_mfma_f32_32x32x16_bf16 v[64:79], v[164:167], v[120:123], v[64:79]
	v_exp_f32_e32 v81, v84
	v_exp_f32_e32 v82, v85
	v_add_f32_e32 v80, v81, v80
	v_cvt_pk_bf16_f32 v98, v81, v82
	v_add_f32_e32 v80, v82, v80
	v_mfma_f32_32x32x16_bf16 v[64:79], v[108:111], v[124:127], v[64:79]
	v_exp_f32_e32 v81, v86
	v_exp_f32_e32 v82, v87
	v_add_f32_e32 v80, v81, v80
	v_cvt_pk_bf16_f32 v99, v81, v82
	v_add_f32_e32 v80, v82, v80
	s_waitcnt lgkmcnt(4)
	v_mfma_f32_32x32x16_bf16 v[64:79], v[186:189], v[128:131], v[64:79]
	v_exp_f32_e32 v81, v88
	v_exp_f32_e32 v82, v89
	v_add_f32_e32 v80, v81, v80
	v_cvt_pk_bf16_f32 v100, v81, v82
	v_add_f32_e32 v80, v82, v80
	s_waitcnt lgkmcnt(0)
	v_mfma_f32_32x32x16_bf16 v[48:63], v[190:193], v[112:115], v[48:63]
	v_exp_f32_e32 v81, v90
	v_exp_f32_e32 v82, v91
	v_add_f32_e32 v80, v81, v80
	v_cvt_pk_bf16_f32 v101, v81, v82
	v_add_f32_e32 v80, v82, v80
	v_mfma_f32_32x32x16_bf16 v[48:63], v[194:197], v[104:107], v[48:63]
	v_exp_f32_e32 v81, v92
	v_exp_f32_e32 v82, v93
	v_add_f32_e32 v80, v81, v80
	v_cvt_pk_bf16_f32 v102, v81, v82
	v_add_f32_e32 v80, v82, v80
	v_mfma_f32_32x32x16_bf16 v[32:47], v[198:201], v[112:115], v[32:47]
	v_exp_f32_e32 v81, v94
	v_exp_f32_e32 v82, v95
	v_add_f32_e32 v80, v81, v80
	v_cvt_pk_bf16_f32 v103, v81, v82
	v_add_f32_e32 v164, v82, v80
	v_exp_f32_e32 v64, v64
	v_exp_f32_e32 v65, v65
	v_mfma_f32_32x32x16_bf16 v[32:47], v[230:233], v[104:107], v[32:47]
	v_add_f32_e32 v165, v65, v64
	v_cvt_pk_bf16_f32 v186, v64, v65
	ds_read_b128 v[80:83], v168 offset:4608
	ds_read_b128 v[112:115], v168 offset:4640
	ds_read_b128 v[108:111], v168 offset:4672
	v_cmp_nge_f32_e64 s[8:9], s62, v164
	v_cmp_gt_f32_e32 vcc, s75, v164
	s_and_b64 s[6:7], s[6:7], vcc
	s_or_b64 s[6:7], s[6:7], s[8:9]
	ds_read_b128 v[104:107], v168 offset:4704
	s_waitcnt lgkmcnt(1)
	v_mfma_f32_32x32x16_bf16 v[80:95], v[80:83], v[148:151], 0
	ds_read_b128 v[190:193], v168 offset:9216
	ds_read_b128 v[194:197], v168 offset:9248
	ds_read_b128 v[198:201], v168 offset:13824
	ds_read_b128 v[230:233], v168 offset:13856
	v_exp_f32_e32 v64, v66
	v_exp_f32_e32 v65, v67
	v_add_f32_e32 v66, v64, v165
	v_add_f32_e32 v66, v65, v66
	v_cvt_pk_bf16_f32 v187, v64, v65
	v_mfma_f32_32x32x16_bf16 v[80:95], v[112:115], v[152:155], v[80:95]
	v_exp_f32_e32 v64, v68
	v_exp_f32_e32 v65, v69
	v_add_f32_e32 v66, v64, v66
	v_cvt_pk_bf16_f32 v188, v64, v65
	v_add_f32_e32 v64, v65, v66
	v_mfma_f32_32x32x16_bf16 v[80:95], v[108:111], v[156:159], v[80:95]
	v_exp_f32_e32 v65, v70
	v_exp_f32_e32 v66, v71
	v_add_f32_e32 v64, v65, v64
	v_cvt_pk_bf16_f32 v189, v65, v66
	v_add_f32_e32 v64, v66, v64
	s_waitcnt lgkmcnt(4)
	v_mfma_f32_32x32x16_bf16 v[80:95], v[104:107], v[160:163], v[80:95]
	v_exp_f32_e32 v65, v72
	v_exp_f32_e32 v66, v73
	v_add_f32_e32 v64, v65, v64
	v_cvt_pk_bf16_f32 v108, v65, v66
	v_add_f32_e32 v64, v66, v64
	s_waitcnt lgkmcnt(0)
	v_mfma_f32_32x32x16_bf16 v[16:31], v[190:193], v[96:99], v[16:31]
	v_exp_f32_e32 v65, v74
	v_exp_f32_e32 v66, v75
	v_add_f32_e32 v64, v65, v64
	v_cvt_pk_bf16_f32 v109, v65, v66
	v_add_f32_e32 v64, v66, v64
	v_mfma_f32_32x32x16_bf16 v[16:31], v[194:197], v[100:103], v[16:31]
	v_exp_f32_e32 v65, v76
	v_exp_f32_e32 v66, v77
	v_add_f32_e32 v64, v65, v64
	v_cvt_pk_bf16_f32 v110, v65, v66
	v_add_f32_e32 v64, v66, v64
	v_mfma_f32_32x32x16_bf16 v[0:15], v[198:201], v[96:99], v[0:15]
	v_exp_f32_e32 v65, v78
	v_exp_f32_e32 v66, v79
	v_add_f32_e32 v64, v65, v64
	v_cvt_pk_bf16_f32 v111, v65, v66
	v_add_f32_e32 v104, v66, v64
	v_exp_f32_e32 v68, v80
	v_exp_f32_e32 v69, v81
	v_mfma_f32_32x32x16_bf16 v[0:15], v[230:233], v[100:103], v[0:15]
	v_add_f32_e32 v81, v69, v68
	v_cvt_pk_bf16_f32 v80, v68, v69
	ds_read_b128 v[64:67], v168 offset:18432
	ds_read_b128 v[96:99], v168 offset:18464
	ds_read_b128 v[112:115], v168 offset:18496
	v_cmp_nge_f32_e64 s[8:9], s62, v104
	ds_read_b128 v[100:103], v168 offset:18528
	s_waitcnt lgkmcnt(1)
	v_mfma_f32_32x32x16_bf16 v[64:79], v[64:67], v[116:119], 0
	ds_read_b128 v[190:193], v168 offset:9280
	ds_read_b128 v[194:197], v168 offset:9312
	ds_read_b128 v[198:201], v168 offset:13888
	ds_read_b128 v[230:233], v168 offset:13920
	v_exp_f32_e32 v82, v82
	v_exp_f32_e32 v83, v83
	v_add_f32_e32 v81, v82, v81
	v_add_f32_e32 v105, v83, v81
	v_cvt_pk_bf16_f32 v81, v82, v83
	v_mfma_f32_32x32x16_bf16 v[64:79], v[96:99], v[120:123], v[64:79]
	v_exp_f32_e32 v82, v84
	v_exp_f32_e32 v83, v85
	v_add_f32_e32 v84, v82, v105
	v_cvt_pk_bf16_f32 v82, v82, v83
	v_add_f32_e32 v83, v83, v84
	v_mfma_f32_32x32x16_bf16 v[64:79], v[112:115], v[124:127], v[64:79]
	v_exp_f32_e32 v84, v86
	v_exp_f32_e32 v85, v87
	v_add_f32_e32 v86, v84, v83
	v_cvt_pk_bf16_f32 v83, v84, v85
	v_add_f32_e32 v84, v85, v86
	s_waitcnt lgkmcnt(4)
	v_mfma_f32_32x32x16_bf16 v[64:79], v[100:103], v[128:131], v[64:79]
	v_exp_f32_e32 v85, v88
	v_exp_f32_e32 v86, v89
	v_add_f32_e32 v87, v85, v84
	v_cvt_pk_bf16_f32 v84, v85, v86
	v_add_f32_e32 v85, v86, v87
	s_waitcnt lgkmcnt(0)
	v_mfma_f32_32x32x16_bf16 v[48:63], v[190:193], v[186:189], v[48:63]
	v_exp_f32_e32 v86, v90
	v_exp_f32_e32 v87, v91
	v_add_f32_e32 v88, v86, v85
	v_cvt_pk_bf16_f32 v85, v86, v87
	v_add_f32_e32 v86, v87, v88
	v_mfma_f32_32x32x16_bf16 v[48:63], v[194:197], v[108:111], v[48:63]
	v_exp_f32_e32 v87, v92
	v_exp_f32_e32 v88, v93
	v_add_f32_e32 v89, v87, v86
	v_cvt_pk_bf16_f32 v86, v87, v88
	v_add_f32_e32 v87, v88, v89
	v_mfma_f32_32x32x16_bf16 v[32:47], v[198:201], v[186:189], v[32:47]
	v_exp_f32_e32 v88, v94
	v_exp_f32_e32 v89, v95
	v_add_f32_e32 v90, v88, v87
	v_cvt_pk_bf16_f32 v87, v88, v89
	v_add_f32_e32 v105, v89, v90
	v_mfma_f32_32x32x16_bf16 v[32:47], v[230:233], v[108:111], v[32:47]
	ds_read_b128 v[96:99], v168 offset:18432
	ds_read_b128 v[92:95], v168 offset:18464
	ds_read_b128 v[88:91], v168 offset:18496
	v_cmp_nge_f32_e64 s[10:11], s62, v105
	s_barrier
	s_waitcnt lgkmcnt(0)
	s_cmpk_gt_u32 s33, 0xfc
	s_cbranch_scc1 .LBB0_447
	v_add_u32_e32 v100, s49, v173
	s_waitcnt vmcnt(0)
	ds_write_b128 v100, v[140:143]
	ds_write_b128 v100, v[144:147] offset:9216

.LBB0_927:
	s_add_i32 s6, s61, -1
	s_and_b32 s77, s61, 2
	s_and_b32 s79, s6, 3
	s_cmp_eq_u32 s61, 0
	s_cselect_b64 s[8:9], -1, 0
	s_mulk_i32 s79, 0x5800
	s_and_b64 s[6:7], s[8:9], exec
	s_mul_i32 s78, s77, 0x5800
	s_cselect_b32 s6, 0, s79
	s_add_i32 s76, s78, 0
	v_add_u32_e32 v199, s76, v241
	v_exp_f32_e32 v64, v64
	v_exp_f32_e32 v65, v65
	v_add_u32_e32 v210, s6, v244
	v_add_f32_e32 v84, v65, v64
	v_cvt_pk_bf16_f32 v178, v64, v65
	v_exp_f32_e32 v64, v66
	ds_read_b128 v[182:185], v199 offset:96
	ds_read_b128 v[246:249], v199 offset:128
	ds_read_b128 v[250:253], v199 offset:160
	v_exp_f32_e32 v65, v67
	v_add_f32_e32 v66, v64, v84
	v_mfma_f32_32x32x16_bf16 v[80:95], v[80:83], v[122:125], 0
	v_add_f32_e32 v66, v65, v66
	v_cvt_pk_bf16_f32 v179, v64, v65
	v_mfma_f32_32x32x16_bf16 v[80:95], v[174:177], v[126:129], v[80:95]
	v_exp_f32_e32 v64, v68
	v_exp_f32_e32 v65, v69
	v_add_f32_e32 v66, v64, v66
	v_add_f32_e32 v66, v65, v66
	v_cvt_pk_bf16_f32 v180, v64, v65
	v_mfma_f32_32x32x16_bf16 v[80:95], v[170:173], v[130:133], v[80:95]
	v_exp_f32_e32 v64, v70
	v_exp_f32_e32 v65, v71
	v_add_f32_e32 v66, v64, v66
	v_add_f32_e32 v170, v65, v66
	v_cvt_pk_bf16_f32 v181, v64, v65
	s_waitcnt lgkmcnt(0)
	v_mfma_f32_32x32x16_bf16 v[80:95], v[182:185], v[134:137], v[80:95]
	ds_read_b128 v[64:67], v210 offset:13376
	ds_read_b128 v[68:71], v210 offset:13408
	ds_read_b128 v[174:177], v210 offset:17984
	ds_read_b128 v[218:221], v210 offset:18016
	v_exp_f32_e32 v72, v72
	v_exp_f32_e32 v73, v73
	v_add_f32_e32 v170, v72, v170
	v_add_f32_e32 v171, v73, v170
	v_cvt_pk_bf16_f32 v170, v72, v73
	v_mfma_f32_32x32x16_bf16 v[80:95], v[246:249], v[154:157], v[80:95]
	v_exp_f32_e32 v72, v74
	v_exp_f32_e32 v73, v75
	v_add_f32_e32 v74, v72, v171
	v_add_f32_e32 v74, v73, v74
	v_cvt_pk_bf16_f32 v171, v72, v73
	v_mfma_f32_32x32x16_bf16 v[80:95], v[250:253], v[158:161], v[80:95]
	v_exp_f32_e32 v72, v76
	v_exp_f32_e32 v73, v77
	v_add_f32_e32 v74, v72, v74
	v_add_f32_e32 v74, v73, v74
	v_cvt_pk_bf16_f32 v172, v72, v73
	s_waitcnt lgkmcnt(0)
	v_mfma_f32_32x32x16_bf16 v[16:31], v[64:67], v[162:165], v[16:31]
	v_exp_f32_e32 v64, v78
	v_exp_f32_e32 v65, v79
	v_add_f32_e32 v66, v64, v74
	v_add_f32_e32 v246, v65, v66
	v_cvt_pk_bf16_f32 v173, v64, v65
	v_mfma_f32_32x32x16_bf16 v[0:15], v[174:177], v[162:165], v[0:15]
	ds_read_b128 v[64:67], v199 offset:6656
	ds_read_b128 v[182:185], v199 offset:6688
	ds_read_b128 v[174:177], v199 offset:6720
	v_cmp_nge_f32_e64 s[6:7], s48, v246
	v_cmp_gt_f32_e32 vcc, s49, v246
	v_mfma_f32_32x32x16_bf16 v[16:31], v[68:71], v[166:169], v[16:31]
	v_exp_f32_e32 v68, v80
	v_exp_f32_e32 v69, v81
	v_exp_f32_e32 v80, v82
	v_add_f32_e32 v70, v69, v68
	v_cvt_pk_bf16_f32 v162, v68, v69
	v_exp_f32_e32 v81, v83
	v_add_f32_e32 v82, v80, v70
	v_mfma_f32_32x32x16_bf16 v[0:15], v[218:221], v[166:169], v[0:15]
	s_and_b64 vcc, s[8:9], vcc
	s_or_b64 s[6:7], s[6:7], vcc
	v_add_u32_e32 v211, s76, v243
	ds_read_b128 v[166:169], v199 offset:6752
	ds_read_b128 v[218:221], v199 offset:6784
	ds_read_b128 v[248:251], v199 offset:6816
	s_waitcnt lgkmcnt(3)
	v_mfma_f32_32x32x16_bf16 v[64:79], v[64:67], v[98:101], 0
	v_add_f32_e32 v82, v81, v82
	v_cvt_pk_bf16_f32 v163, v80, v81
	v_mfma_f32_32x32x16_bf16 v[64:79], v[182:185], v[102:105], v[64:79]
	v_exp_f32_e32 v80, v84
	v_exp_f32_e32 v81, v85
	v_add_f32_e32 v82, v80, v82
	v_add_f32_e32 v82, v81, v82
	v_cvt_pk_bf16_f32 v164, v80, v81
	v_mfma_f32_32x32x16_bf16 v[64:79], v[174:177], v[106:109], v[64:79]
	v_exp_f32_e32 v80, v86
	v_exp_f32_e32 v81, v87
	v_add_f32_e32 v82, v80, v82
	v_add_f32_e32 v174, v81, v82
	v_cvt_pk_bf16_f32 v165, v80, v81
	s_waitcnt lgkmcnt(0)
	v_mfma_f32_32x32x16_bf16 v[64:79], v[166:169], v[110:113], v[64:79]
	ds_read_b128 v[80:83], v211 offset:13312
	ds_read_b128 v[84:87], v211 offset:13344
	ds_read_b128 v[182:185], v211 offset:17920
	ds_read_b128 v[222:225], v211 offset:17952
	v_exp_f32_e32 v88, v88
	v_exp_f32_e32 v89, v89
	v_add_f32_e32 v166, v88, v174
	v_add_f32_e32 v166, v89, v166
	v_cvt_pk_bf16_f32 v174, v88, v89
	v_mfma_f32_32x32x16_bf16 v[64:79], v[218:221], v[114:117], v[64:79]
	v_exp_f32_e32 v88, v90
	v_exp_f32_e32 v89, v91
	v_add_f32_e32 v90, v88, v166
	v_add_f32_e32 v90, v89, v90
	v_cvt_pk_bf16_f32 v175, v88, v89
	v_mfma_f32_32x32x16_bf16 v[64:79], v[248:251], v[118:121], v[64:79]
	v_exp_f32_e32 v88, v92
	v_exp_f32_e32 v89, v93
	v_add_f32_e32 v90, v88, v90
	v_add_f32_e32 v90, v89, v90
	v_cvt_pk_bf16_f32 v176, v88, v89
	s_waitcnt lgkmcnt(0)
	v_mfma_f32_32x32x16_bf16 v[48:63], v[80:83], v[178:181], v[48:63]
	v_exp_f32_e32 v80, v94
	v_exp_f32_e32 v81, v95
	v_add_f32_e32 v82, v80, v90
	v_add_f32_e32 v247, v81, v82
	v_cvt_pk_bf16_f32 v177, v80, v81
	v_mfma_f32_32x32x16_bf16 v[32:47], v[182:185], v[178:181], v[32:47]
	ds_read_b128 v[80:83], v199 offset:6656
	ds_read_b128 v[182:185], v199 offset:6688
	ds_read_b128 v[178:181], v199 offset:6720
	v_cmp_nge_f32_e64 s[10:11], s48, v247
	v_cmp_gt_f32_e32 vcc, s49, v247
	v_mfma_f32_32x32x16_bf16 v[48:63], v[84:87], v[170:173], v[48:63]
	v_exp_f32_e32 v64, v64
	v_exp_f32_e32 v65, v65
	s_nop 0
	v_add_f32_e32 v84, v65, v64
	v_cvt_pk_bf16_f32 v166, v64, v65
	v_exp_f32_e32 v64, v66
	v_exp_f32_e32 v65, v67
	v_add_f32_e32 v66, v64, v84
	v_mfma_f32_32x32x16_bf16 v[32:47], v[222:225], v[170:173], v[32:47]
	s_and_b64 s[8:9], s[8:9], vcc
	s_or_b64 s[8:9], s[8:9], s[10:11]
	ds_read_b128 v[170:173], v199 offset:6752
	ds_read_b128 v[218:221], v199 offset:6784
	ds_read_b128 v[222:225], v199 offset:6816
	s_waitcnt lgkmcnt(3)
	v_mfma_f32_32x32x16_bf16 v[80:95], v[80:83], v[122:125], 0
	v_add_f32_e32 v66, v65, v66
	v_cvt_pk_bf16_f32 v167, v64, v65
	v_mfma_f32_32x32x16_bf16 v[80:95], v[182:185], v[126:129], v[80:95]
	v_exp_f32_e32 v64, v68
	v_exp_f32_e32 v65, v69
	v_add_f32_e32 v66, v64, v66
	v_add_f32_e32 v66, v65, v66
	v_cvt_pk_bf16_f32 v168, v64, v65
	v_mfma_f32_32x32x16_bf16 v[80:95], v[178:181], v[130:133], v[80:95]
	v_exp_f32_e32 v64, v70
	v_exp_f32_e32 v65, v71
	v_add_f32_e32 v66, v64, v66
	v_add_f32_e32 v178, v65, v66
	v_cvt_pk_bf16_f32 v169, v64, v65
	s_waitcnt lgkmcnt(0)
	v_mfma_f32_32x32x16_bf16 v[80:95], v[170:173], v[134:137], v[80:95]
	ds_read_b128 v[64:67], v211 offset:13312
	ds_read_b128 v[68:71], v211 offset:13344
	ds_read_b128 v[182:185], v211 offset:17920
	ds_read_b128 v[248:251], v211 offset:17952
	v_exp_f32_e32 v72, v72
	v_exp_f32_e32 v73, v73
	v_add_f32_e32 v170, v72, v178
	v_add_f32_e32 v170, v73, v170
	v_cvt_pk_bf16_f32 v178, v72, v73
	v_mfma_f32_32x32x16_bf16 v[80:95], v[218:221], v[154:157], v[80:95]
	v_exp_f32_e32 v72, v74
	v_exp_f32_e32 v73, v75
	v_add_f32_e32 v74, v72, v170
	v_add_f32_e32 v74, v73, v74
	v_cvt_pk_bf16_f32 v179, v72, v73
	v_mfma_f32_32x32x16_bf16 v[80:95], v[222:225], v[158:161], v[80:95]
	v_exp_f32_e32 v72, v76
	v_exp_f32_e32 v73, v77
	v_add_f32_e32 v74, v72, v74
	v_add_f32_e32 v74, v73, v74
	v_cvt_pk_bf16_f32 v180, v72, v73
	s_waitcnt lgkmcnt(0)
	v_mfma_f32_32x32x16_bf16 v[16:31], v[64:67], v[162:165], v[16:31]
	v_exp_f32_e32 v64, v78
	v_exp_f32_e32 v65, v79
	v_add_f32_e32 v66, v64, v74
	v_add_f32_e32 v210, v65, v66
	v_cvt_pk_bf16_f32 v181, v64, v65
	v_mfma_f32_32x32x16_bf16 v[0:15], v[182:185], v[162:165], v[0:15]
	v_add_u32_e32 v226, s78, v242
	ds_read_b128 v[64:67], v226 offset:22528
	ds_read_b128 v[170:173], v226 offset:22560
	ds_read_b128 v[182:185], v226 offset:22592
	v_cmp_nge_f32_e64 s[10:11], s48, v210
	v_mfma_f32_32x32x16_bf16 v[16:31], v[68:71], v[174:177], v[16:31]
	v_exp_f32_e32 v68, v80
	v_exp_f32_e32 v69, v81
	v_exp_f32_e32 v80, v82
	v_add_f32_e32 v70, v69, v68
	v_cvt_pk_bf16_f32 v162, v68, v69
	v_exp_f32_e32 v81, v83
	v_add_f32_e32 v82, v80, v70
	v_mfma_f32_32x32x16_bf16 v[0:15], v[248:251], v[174:177], v[0:15]
	ds_read_b128 v[174:177], v226 offset:22624
	ds_read_b128 v[218:221], v226 offset:22656
	ds_read_b128 v[222:225], v226 offset:22688
	s_waitcnt lgkmcnt(3)
	v_mfma_f32_32x32x16_bf16 v[64:79], v[64:67], v[98:101], 0
	v_add_f32_e32 v82, v81, v82
	v_cvt_pk_bf16_f32 v163, v80, v81
	v_mfma_f32_32x32x16_bf16 v[64:79], v[170:173], v[102:105], v[64:79]
	v_exp_f32_e32 v80, v84
	v_exp_f32_e32 v81, v85
	v_add_f32_e32 v82, v80, v82
	v_add_f32_e32 v82, v81, v82
	v_cvt_pk_bf16_f32 v164, v80, v81
	v_mfma_f32_32x32x16_bf16 v[64:79], v[182:185], v[106:109], v[64:79]
	v_exp_f32_e32 v80, v86
	v_exp_f32_e32 v81, v87
	v_add_f32_e32 v82, v80, v82
	v_add_f32_e32 v170, v81, v82
	v_cvt_pk_bf16_f32 v165, v80, v81
	s_waitcnt lgkmcnt(0)
	v_mfma_f32_32x32x16_bf16 v[64:79], v[174:177], v[110:113], v[64:79]
	ds_read_b128 v[80:83], v211 offset:13376
	ds_read_b128 v[84:87], v211 offset:13408
	ds_read_b128 v[182:185], v211 offset:17984
	ds_read_b128 v[248:251], v211 offset:18016
	v_exp_f32_e32 v88, v88
	v_exp_f32_e32 v89, v89
	v_add_f32_e32 v170, v88, v170
	v_add_f32_e32 v171, v89, v170
	v_cvt_pk_bf16_f32 v170, v88, v89
	v_mfma_f32_32x32x16_bf16 v[64:79], v[218:221], v[114:117], v[64:79]
	v_exp_f32_e32 v88, v90
	v_exp_f32_e32 v89, v91
	v_add_f32_e32 v90, v88, v171
	v_add_f32_e32 v90, v89, v90
	v_cvt_pk_bf16_f32 v171, v88, v89
	v_mfma_f32_32x32x16_bf16 v[64:79], v[222:225], v[118:121], v[64:79]
	v_exp_f32_e32 v88, v92
	v_exp_f32_e32 v89, v93
	v_add_f32_e32 v90, v88, v90
	v_add_f32_e32 v90, v89, v90
	v_cvt_pk_bf16_f32 v172, v88, v89
	s_waitcnt lgkmcnt(0)
	v_mfma_f32_32x32x16_bf16 v[48:63], v[80:83], v[166:169], v[48:63]
	v_exp_f32_e32 v80, v94
	v_exp_f32_e32 v81, v95
	v_add_f32_e32 v82, v80, v90
	v_add_f32_e32 v211, v81, v82
	v_cvt_pk_bf16_f32 v173, v80, v81
	v_mfma_f32_32x32x16_bf16 v[32:47], v[182:185], v[166:169], v[32:47]
	ds_read_b128 v[80:83], v226 offset:22528
	ds_read_b128 v[182:185], v226 offset:22560
	ds_read_b128 v[174:177], v226 offset:22592
	v_cmp_nge_f32_e64 s[12:13], s48, v211
	v_mfma_f32_32x32x16_bf16 v[48:63], v[84:87], v[178:181], v[48:63]
	s_barrier
	s_waitcnt lgkmcnt(0)
	v_mfma_f32_32x32x16_bf16 v[32:47], v[248:251], v[178:181], v[32:47]
	s_cmpk_gt_u32 s61, 0xfc
	s_cbranch_scc1 .LBB0_933
	s_add_i32 s24, s79, 0
	v_add_u32_e32 v84, s24, v238
	v_add_u32_e32 v85, s24, v245
	v_add_u32_e32 v86, s24, v198
	s_waitcnt vmcnt(0)
	ds_write_b128 v84, v[150:153]
	ds_write_b64 v85, v[190:191] offset:128
	ds_write_b128 v86, v[138:141] offset:13312

.LBB0_935:
	s_or_b64 s[6:7], s[8:9], s[6:7]
	v_add_f32_e32 v84, v204, v246
	v_add_f32_e32 v85, v205, v247
	s_or_b64 s[6:7], s[6:7], s[10:11]
	s_or_b64 s[6:7], s[6:7], s[12:13]
	v_add_f32_e32 v178, v84, v210
	v_add_f32_e32 v179, v85, v211
	s_xor_b32 s10, s77, 2
	v_exp_f32_e32 v64, v64
	v_exp_f32_e32 v65, v65
	v_add_u32_e32 v222, s78, v244
	v_add_f32_e32 v84, v65, v64
	v_cvt_pk_bf16_f32 v166, v64, v65
	v_exp_f32_e32 v64, v66
	ds_read_b128 v[204:207], v199 offset:22624
	ds_read_b128 v[208:211], v199 offset:22656
	ds_read_b128 v[218:221], v199 offset:22688
	v_exp_f32_e32 v65, v67
	v_add_f32_e32 v66, v64, v84
	v_mfma_f32_32x32x16_bf16 v[80:95], v[80:83], v[122:125], 0
	v_add_f32_e32 v66, v65, v66
	v_cvt_pk_bf16_f32 v167, v64, v65
	v_mfma_f32_32x32x16_bf16 v[80:95], v[182:185], v[126:129], v[80:95]
	v_exp_f32_e32 v64, v68
	v_exp_f32_e32 v65, v69
	v_add_f32_e32 v66, v64, v66
	v_add_f32_e32 v66, v65, v66
	v_cvt_pk_bf16_f32 v168, v64, v65
	v_mfma_f32_32x32x16_bf16 v[80:95], v[174:177], v[130:133], v[80:95]
	v_exp_f32_e32 v64, v70
	v_exp_f32_e32 v65, v71
	v_add_f32_e32 v66, v64, v66
	v_add_f32_e32 v174, v65, v66
	v_cvt_pk_bf16_f32 v169, v64, v65
	s_waitcnt lgkmcnt(0)
	v_mfma_f32_32x32x16_bf16 v[80:95], v[204:207], v[134:137], v[80:95]
	ds_read_b128 v[64:67], v222 offset:13376
	ds_read_b128 v[68:71], v222 offset:13408
	ds_read_b128 v[180:183], v222 offset:17984
	ds_read_b128 v[222:225], v222 offset:18016
	v_exp_f32_e32 v72, v72
	v_exp_f32_e32 v73, v73
	v_add_f32_e32 v174, v72, v174
	v_add_f32_e32 v175, v73, v174
	v_cvt_pk_bf16_f32 v174, v72, v73
	v_mfma_f32_32x32x16_bf16 v[80:95], v[208:211], v[154:157], v[80:95]
	v_exp_f32_e32 v72, v74
	v_exp_f32_e32 v73, v75
	v_add_f32_e32 v74, v72, v175
	v_add_f32_e32 v74, v73, v74
	v_cvt_pk_bf16_f32 v175, v72, v73
	v_mfma_f32_32x32x16_bf16 v[80:95], v[218:221], v[158:161], v[80:95]
	v_exp_f32_e32 v72, v76
	v_exp_f32_e32 v73, v77
	v_add_f32_e32 v74, v72, v74
	v_add_f32_e32 v74, v73, v74
	v_cvt_pk_bf16_f32 v176, v72, v73
	s_waitcnt lgkmcnt(0)
	v_mfma_f32_32x32x16_bf16 v[16:31], v[64:67], v[162:165], v[16:31]
	v_exp_f32_e32 v64, v78
	v_exp_f32_e32 v65, v79
	v_add_f32_e32 v66, v64, v74
	v_add_f32_e32 v204, v65, v66
	v_cvt_pk_bf16_f32 v177, v64, v65
	v_mfma_f32_32x32x16_bf16 v[0:15], v[180:183], v[162:165], v[0:15]
	ds_read_b128 v[64:67], v199 offset:29184
	ds_read_b128 v[180:183], v199 offset:29216
	ds_read_b128 v[208:211], v199 offset:29248
	v_cmp_nge_f32_e32 vcc, s48, v204
	v_mfma_f32_32x32x16_bf16 v[16:31], v[68:71], v[170:173], v[16:31]
	v_mfma_f32_32x32x16_bf16 v[0:15], v[222:225], v[170:173], v[0:15]
	v_mad_u32_u24 v68, v187, s69, v186
	v_add_u32_e32 v206, s76, v68
	v_exp_f32_e32 v68, v80
	v_exp_f32_e32 v69, v81
	v_exp_f32_e32 v80, v82
	v_add_f32_e32 v70, v69, v68
	v_cvt_pk_bf16_f32 v162, v68, v69
	ds_read_b128 v[170:173], v199 offset:29280
	ds_read_b128 v[218:221], v199 offset:29312
	ds_read_b128 v[222:225], v199 offset:29344
	v_exp_f32_e32 v81, v83
	v_add_f32_e32 v82, v80, v70
	s_waitcnt lgkmcnt(3)
	v_mfma_f32_32x32x16_bf16 v[64:79], v[64:67], v[98:101], 0
	v_add_f32_e32 v82, v81, v82
	v_cvt_pk_bf16_f32 v163, v80, v81
	v_mfma_f32_32x32x16_bf16 v[64:79], v[180:183], v[102:105], v[64:79]
	v_exp_f32_e32 v80, v84
	v_exp_f32_e32 v81, v85
	v_add_f32_e32 v82, v80, v82
	v_add_f32_e32 v82, v81, v82
	v_cvt_pk_bf16_f32 v164, v80, v81
	v_mfma_f32_32x32x16_bf16 v[64:79], v[208:211], v[106:109], v[64:79]
	v_exp_f32_e32 v80, v86
	v_exp_f32_e32 v81, v87
	v_add_f32_e32 v82, v80, v82
	v_add_f32_e32 v184, v81, v82
	v_cvt_pk_bf16_f32 v165, v80, v81
	s_waitcnt lgkmcnt(0)
	v_mfma_f32_32x32x16_bf16 v[64:79], v[170:173], v[110:113], v[64:79]
	ds_read_b128 v[80:83], v206 offset:35840
	ds_read_b128 v[84:87], v206 offset:35872
	ds_read_b128 v[180:183], v206 offset:40448
	ds_read_b128 v[208:211], v206 offset:40480
	v_exp_f32_e32 v88, v88
	v_exp_f32_e32 v89, v89
	v_add_f32_e32 v170, v88, v184
	v_add_f32_e32 v171, v89, v170
	v_cvt_pk_bf16_f32 v170, v88, v89
	v_mfma_f32_32x32x16_bf16 v[64:79], v[218:221], v[114:117], v[64:79]
	v_exp_f32_e32 v88, v90
	v_exp_f32_e32 v89, v91
	v_add_f32_e32 v90, v88, v171
	v_add_f32_e32 v90, v89, v90
	v_cvt_pk_bf16_f32 v171, v88, v89
	v_mfma_f32_32x32x16_bf16 v[64:79], v[222:225], v[118:121], v[64:79]
	v_exp_f32_e32 v88, v92
	v_exp_f32_e32 v89, v93
	v_add_f32_e32 v90, v88, v90
	v_add_f32_e32 v90, v89, v90
	v_cvt_pk_bf16_f32 v172, v88, v89
	s_waitcnt lgkmcnt(0)
	v_mfma_f32_32x32x16_bf16 v[48:63], v[80:83], v[166:169], v[48:63]
	v_exp_f32_e32 v80, v94
	v_exp_f32_e32 v81, v95
	v_add_f32_e32 v82, v80, v90
	v_add_f32_e32 v205, v81, v82
	v_cvt_pk_bf16_f32 v173, v80, v81
	v_mfma_f32_32x32x16_bf16 v[32:47], v[180:183], v[166:169], v[32:47]
	ds_read_b128 v[80:83], v199 offset:29184
	ds_read_b128 v[166:169], v199 offset:29216
	ds_read_b128 v[182:185], v199 offset:29248
	s_or_b64 s[8:9], s[6:7], vcc
	v_cmp_nge_f32_e32 vcc, s48, v205
	v_add_f32_e32 v204, v178, v204
	v_add_f32_e32 v205, v179, v205
	v_mfma_f32_32x32x16_bf16 v[48:63], v[84:87], v[174:177], v[48:63]
	v_exp_f32_e32 v64, v64
	v_exp_f32_e32 v65, v65
	s_nop 0
	v_add_f32_e32 v84, v65, v64
	v_cvt_pk_bf16_f32 v178, v64, v65
	v_exp_f32_e32 v64, v66
	v_exp_f32_e32 v65, v67
	v_add_f32_e32 v66, v64, v84
	v_mfma_f32_32x32x16_bf16 v[32:47], v[208:211], v[174:177], v[32:47]
	ds_read_b128 v[174:177], v199 offset:29280
	ds_read_b128 v[208:211], v199 offset:29312
	ds_read_b128 v[218:221], v199 offset:29344
	s_waitcnt lgkmcnt(3)
; template <int MODE, bool FAST> __device__ __forceinline__ bool attn_unit(LAS unsigned char* lds, const AttU& U, const int wv) {
;     ...
;         for (int t2 = U.kt0; t2 < U.kt1; t2 += 2) { ATT_TILE(t2, 4, rk, rr, rv); ATT_TILE(t2 + 1, 4, rk2, rr2, rv2); }
	v_mfma_f32_32x32x16_bf16 v[80:95], v[80:83], v[122:125], 0
	v_add_f32_e32 v66, v65, v66
	v_cvt_pk_bf16_f32 v179, v64, v65
	v_mfma_f32_32x32x16_bf16 v[80:95], v[166:169], v[126:129], v[80:95]
	v_exp_f32_e32 v64, v68
	v_exp_f32_e32 v65, v69
	v_add_f32_e32 v66, v64, v66
	v_add_f32_e32 v66, v65, v66
	v_cvt_pk_bf16_f32 v180, v64, v65
	v_mfma_f32_32x32x16_bf16 v[80:95], v[182:185], v[130:133], v[80:95]
	v_exp_f32_e32 v64, v70
	v_exp_f32_e32 v65, v71
	v_add_f32_e32 v66, v64, v66
	v_add_f32_e32 v182, v65, v66
	v_cvt_pk_bf16_f32 v181, v64, v65
	s_waitcnt lgkmcnt(0)
	v_mfma_f32_32x32x16_bf16 v[80:95], v[174:177], v[134:137], v[80:95]
	ds_read_b128 v[64:67], v206 offset:35840
	ds_read_b128 v[68:71], v206 offset:35872
	ds_read_b128 v[166:169], v206 offset:40448
	ds_read_b128 v[222:225], v206 offset:40480
	v_exp_f32_e32 v72, v72
	v_exp_f32_e32 v73, v73
	v_add_f32_e32 v174, v72, v182
	v_add_f32_e32 v174, v73, v174
	v_cvt_pk_bf16_f32 v182, v72, v73
	v_mfma_f32_32x32x16_bf16 v[80:95], v[208:211], v[154:157], v[80:95]
	v_exp_f32_e32 v72, v74
	v_exp_f32_e32 v73, v75
	v_add_f32_e32 v74, v72, v174
	v_add_f32_e32 v74, v73, v74
	v_cvt_pk_bf16_f32 v183, v72, v73
	v_mfma_f32_32x32x16_bf16 v[80:95], v[218:221], v[158:161], v[80:95]
	v_exp_f32_e32 v72, v76
	v_exp_f32_e32 v73, v77
	v_add_f32_e32 v74, v72, v74
	v_add_f32_e32 v74, v73, v74
	v_cvt_pk_bf16_f32 v184, v72, v73
	s_waitcnt lgkmcnt(0)
	v_mfma_f32_32x32x16_bf16 v[16:31], v[64:67], v[162:165], v[16:31]
	v_exp_f32_e32 v64, v78
	v_exp_f32_e32 v65, v79
	v_add_f32_e32 v66, v64, v74
	v_add_f32_e32 v226, v65, v66
	v_cvt_pk_bf16_f32 v185, v64, v65
	v_mfma_f32_32x32x16_bf16 v[0:15], v[166:169], v[162:165], v[0:15]
	s_mulk_i32 s10, 0x5800
	v_add_u32_e32 v199, s10, v242
	ds_read_b128 v[64:67], v199
	ds_read_b128 v[164:167], v199 offset:32
	ds_read_b128 v[174:177], v199 offset:64
	v_cmp_nge_f32_e64 s[6:7], s48, v226
	v_mfma_f32_32x32x16_bf16 v[16:31], v[68:71], v[170:173], v[16:31]
	v_exp_f32_e32 v68, v80
	v_exp_f32_e32 v69, v81
	v_exp_f32_e32 v80, v82
	v_add_f32_e32 v70, v69, v68
	v_cvt_pk_bf16_f32 v162, v68, v69
	v_exp_f32_e32 v81, v83
	v_add_f32_e32 v82, v80, v70
	v_mfma_f32_32x32x16_bf16 v[0:15], v[222:225], v[170:173], v[0:15]
	s_or_b64 s[8:9], s[8:9], vcc
	ds_read_b128 v[168:171], v199 offset:96
	ds_read_b128 v[208:211], v199 offset:128
	ds_read_b128 v[218:221], v199 offset:160
	s_waitcnt lgkmcnt(3)
	v_mfma_f32_32x32x16_bf16 v[64:79], v[64:67], v[98:101], 0
	v_add_f32_e32 v82, v81, v82
	v_cvt_pk_bf16_f32 v163, v80, v81
	v_mfma_f32_32x32x16_bf16 v[64:79], v[164:167], v[102:105], v[64:79]
	v_exp_f32_e32 v80, v84
	v_exp_f32_e32 v81, v85
	v_add_f32_e32 v82, v80, v82
	v_add_f32_e32 v82, v81, v82
	v_cvt_pk_bf16_f32 v164, v80, v81
	v_mfma_f32_32x32x16_bf16 v[64:79], v[174:177], v[106:109], v[64:79]
	v_exp_f32_e32 v80, v86
	v_exp_f32_e32 v81, v87
	v_add_f32_e32 v82, v80, v82
	v_add_f32_e32 v166, v81, v82
	v_cvt_pk_bf16_f32 v165, v80, v81
	s_waitcnt lgkmcnt(0)
	v_mfma_f32_32x32x16_bf16 v[64:79], v[168:171], v[110:113], v[64:79]
	ds_read_b128 v[80:83], v206 offset:35904
	ds_read_b128 v[84:87], v206 offset:35936
	ds_read_b128 v[222:225], v206 offset:40512
	ds_read_b128 v[246:249], v206 offset:40544
	v_exp_f32_e32 v88, v88
	v_exp_f32_e32 v89, v89
	v_add_f32_e32 v166, v88, v166
	v_add_f32_e32 v167, v89, v166
	v_cvt_pk_bf16_f32 v166, v88, v89
	v_mfma_f32_32x32x16_bf16 v[64:79], v[208:211], v[114:117], v[64:79]
	v_exp_f32_e32 v88, v90
	v_exp_f32_e32 v89, v91
	v_add_f32_e32 v90, v88, v167
	v_add_f32_e32 v90, v89, v90
	v_cvt_pk_bf16_f32 v167, v88, v89
	v_mfma_f32_32x32x16_bf16 v[64:79], v[218:221], v[118:121], v[64:79]
	v_exp_f32_e32 v88, v92
	v_exp_f32_e32 v89, v93
	v_add_f32_e32 v90, v88, v90
	v_add_f32_e32 v90, v89, v90
	v_cvt_pk_bf16_f32 v168, v88, v89
	s_waitcnt lgkmcnt(0)
	v_mfma_f32_32x32x16_bf16 v[48:63], v[80:83], v[178:181], v[48:63]
	v_exp_f32_e32 v80, v94
	v_exp_f32_e32 v81, v95
	v_add_f32_e32 v82, v80, v90
	v_add_f32_e32 v227, v81, v82
	v_cvt_pk_bf16_f32 v169, v80, v81
	v_mfma_f32_32x32x16_bf16 v[32:47], v[222:225], v[178:181], v[32:47]
	ds_read_b128 v[80:83], v199
	ds_read_b128 v[174:177], v199 offset:32
	ds_read_b128 v[170:173], v199 offset:64
	s_or_b64 s[6:7], s[8:9], s[6:7]
	v_cmp_nge_f32_e32 vcc, s48, v227
	s_or_b64 s[6:7], s[6:7], vcc
	s_cmp_lg_u64 s[6:7], 0
	s_cselect_b64 s[6:7], -1, 0
	s_or_b64 s[42:43], s[42:43], s[6:7]
	v_mfma_f32_32x32x16_bf16 v[48:63], v[84:87], v[182:185], v[48:63]
	v_add_f32_e32 v204, v204, v226
	v_add_f32_e32 v205, v205, v227
	s_barrier
	s_waitcnt lgkmcnt(0)
	v_mfma_f32_32x32x16_bf16 v[32:47], v[246:249], v[182:185], v[32:47]
	s_add_u32 s40, s40, 0x40000
	s_mov_b64 s[6:7], 0x2000
	s_addc_u32 s41, s41, 0
	v_lshl_add_u64 v[202:203], v[202:203], 0, s[6:7]
	s_and_b64 vcc, exec, s[44:45]
	s_cbranch_vccnz .LBB0_937
	s_mov_b32 s61, s30
	s_branch .LBB0_923
